# attention K/V ring with one workgroup barrier per half-step: barrier1 dropped, V staging writes deferred past the closing barrier, K writes before it
# baseline (speedup 1.0000x reference)
.LBB0_392:
	s_or_b64 exec, exec, s[76:77]
	s_waitcnt lgkmcnt(0)
	s_waitcnt vmcnt(3)
	ds_read_b128 v[18:21], v189 offset:224
	s_waitcnt vmcnt(2)
	ds_read_b128 v[22:25], v189 offset:192
	ds_read_b128 v[26:29], v189 offset:160
	ds_read_b128 v[168:171], v189 offset:128
	s_waitcnt lgkmcnt(3)
	v_pk_mul_f32 v[94:95], v[94:95], v[20:21]
	s_waitcnt lgkmcnt(2)
	v_pk_mul_f32 v[90:91], v[90:91], v[24:25]
	s_waitcnt lgkmcnt(1)
	v_pk_mul_f32 v[86:87], v[86:87], v[28:29]
	s_waitcnt lgkmcnt(0)
	v_pk_mul_f32 v[82:83], v[82:83], v[170:171]
	v_pk_mul_f32 v[92:93], v[92:93], v[18:19]
	v_pk_mul_f32 v[88:89], v[88:89], v[22:23]
	v_pk_mul_f32 v[84:85], v[84:85], v[26:27]
	v_pk_mul_f32 v[80:81], v[80:81], v[168:169]
	v_pk_mul_f32 v[78:79], v[78:79], v[20:21]
	v_pk_mul_f32 v[74:75], v[74:75], v[24:25]
	v_pk_mul_f32 v[70:71], v[70:71], v[28:29]
	v_pk_mul_f32 v[66:67], v[66:67], v[170:171]
	v_pk_mul_f32 v[76:77], v[76:77], v[18:19]
	v_pk_mul_f32 v[72:73], v[72:73], v[22:23]
	v_pk_mul_f32 v[68:69], v[68:69], v[26:27]
	v_pk_mul_f32 v[64:65], v[64:65], v[168:169]
	v_pk_mul_f32 v[62:63], v[62:63], v[20:21]
	v_pk_mul_f32 v[58:59], v[58:59], v[24:25]
	v_pk_mul_f32 v[54:55], v[54:55], v[28:29]
	v_pk_mul_f32 v[50:51], v[50:51], v[170:171]
	v_pk_mul_f32 v[60:61], v[60:61], v[18:19]
	v_pk_mul_f32 v[56:57], v[56:57], v[22:23]
	v_pk_mul_f32 v[52:53], v[52:53], v[26:27]
	v_pk_mul_f32 v[48:49], v[48:49], v[168:169]
	v_pk_mul_f32 v[46:47], v[46:47], v[20:21]
	v_pk_mul_f32 v[42:43], v[42:43], v[24:25]
	v_pk_mul_f32 v[38:39], v[38:39], v[28:29]
	v_pk_mul_f32 v[34:35], v[34:35], v[170:171]
	v_pk_mul_f32 v[44:45], v[44:45], v[18:19]
	v_pk_mul_f32 v[40:41], v[40:41], v[22:23]
	v_pk_mul_f32 v[36:37], v[36:37], v[26:27]
	v_pk_mul_f32 v[32:33], v[32:33], v[168:169]
.LBB0_393:
	v_cndmask_b32_e64 v208, v245, v180, s[10:11]
	v_mul_f32_e32 v254, 0xbdd53b94, v208
	v_mov_b32_e32 v213, v254
	v_fmamk_f32 v224, v112, 0x3dd53b94, v254
	v_fmamk_f32 v226, v113, 0x3dd53b94, v254
	s_waitcnt vmcnt(3)
	v_fmamk_f32 v222, v114, 0x3dd53b94, v254
	v_fmamk_f32 v225, v115, 0x3dd53b94, v254
	v_fmamk_f32 v220, v116, 0x3dd53b94, v254
	v_fmamk_f32 v223, v117, 0x3dd53b94, v254
	s_waitcnt vmcnt(2)
	v_fmamk_f32 v219, v118, 0x3dd53b94, v254
	v_fmamk_f32 v221, v119, 0x3dd53b94, v254
	v_fmamk_f32 v216, v120, 0x3dd53b94, v254
	v_fmamk_f32 v218, v121, 0x3dd53b94, v254
	v_fmamk_f32 v214, v122, 0x3dd53b94, v254
	v_fmamk_f32 v217, v123, 0x3dd53b94, v254
	v_fmamk_f32 v212, v124, 0x3dd53b94, v254
	v_fmamk_f32 v215, v125, 0x3dd53b94, v254
	v_fmamk_f32 v211, v126, 0x3dd53b94, v254
	v_fmac_f32_e32 v213, 0x3dd53b94, v127
	v_exp_f32_e32 v224, v224
	v_exp_f32_e32 v226, v226
	v_exp_f32_e32 v222, v222
	v_exp_f32_e32 v225, v225
	v_exp_f32_e32 v220, v220
	v_exp_f32_e32 v223, v223
	v_exp_f32_e32 v219, v219
	v_exp_f32_e32 v221, v221
	v_exp_f32_e32 v216, v216
	v_exp_f32_e32 v218, v218
	v_exp_f32_e32 v214, v214
	v_exp_f32_e32 v217, v217
	v_exp_f32_e32 v212, v212
	v_exp_f32_e32 v215, v215
	v_exp_f32_e32 v211, v211
	v_exp_f32_e32 v213, v213
	v_add_f32_e32 v0, v0, v14
	s_mov_b64 s[10:11], 0x4000
	v_fmac_f32_e32 v0, v191, v194
	v_add_f32_e32 v194, v17, v30
	v_lshl_add_u64 v[176:177], v[176:177], 0, s[10:11]
	s_mov_b64 s[10:11], 0x200000
	s_addk_i32 s54, 0x80
	s_waitcnt vmcnt(1)
	v_pk_fma_f32 v[160:161], v[110:111], s[30:31], v[254:255] op_sel_hi:[1,0,0]
	v_pk_fma_f32 v[162:163], v[108:109], s[30:31], v[254:255] op_sel_hi:[1,0,0]
	s_waitcnt vmcnt(0)
	v_pk_fma_f32 v[164:165], v[106:107], s[30:31], v[254:255] op_sel_hi:[1,0,0]
	v_pk_fma_f32 v[166:167], v[104:105], s[30:31], v[254:255] op_sel_hi:[1,0,0]
	v_pk_fma_f32 v[168:169], v[102:103], s[30:31], v[254:255] op_sel_hi:[1,0,0]
	v_pk_fma_f32 v[170:171], v[100:101], s[30:31], v[254:255] op_sel_hi:[1,0,0]
	v_pk_fma_f32 v[180:181], v[98:99], s[30:31], v[254:255] op_sel_hi:[1,0,0]
	v_pk_fma_f32 v[182:183], v[96:97], s[30:31], v[254:255] op_sel_hi:[1,0,0]
	v_fmac_f32_e32 v194, v0, v15
	v_lshl_add_u64 v[178:179], v[178:179], 0, s[10:11]
	v_add_u32_e32 v210, 0xffffff80, v210
	v_mov_b32_e32 v191, v235
	s_waitcnt lgkmcnt(0)
	s_barrier
	s_andn2_b64 vcc, exec, s[78:79]
	s_cbranch_vccnz .Lob_h2_nov
	ds_write_b128 v200, v[2:5] offset:16384
	ds_write_b128 v201, v[10:13] offset:16384
.Lob_h2_nov:
	s_cmp_ge_i32 s7, s6
	s_cbranch_scc1 .LBB0_420

.LBB0_401:
	v_max_f32_e32 v15, v113, v113
	v_max_f32_e32 v17, v112, v112
	v_max_f32_e32 v15, v17, v15
	v_max3_f32 v15, v15, v114, v115
	v_max3_f32 v15, v15, v116, v117
	v_max3_f32 v15, v15, v118, v119
	v_max3_f32 v15, v15, v120, v121
	v_max3_f32 v15, v15, v122, v123
	v_max3_f32 v15, v15, v124, v125
	v_max3_f32 v15, v15, v126, v127
	v_max3_f32 v15, v15, v96, v97
	v_max3_f32 v15, v15, v98, v99
	v_max3_f32 v15, v15, v100, v101
	v_max3_f32 v15, v15, v102, v103
	v_max3_f32 v15, v15, v104, v105
	v_max3_f32 v15, v15, v106, v107
	v_max3_f32 v15, v15, v108, v109
	v_max3_f32 v15, v15, v110, v111
	v_mov_b32_e32 v17, v15
	s_nop 1
	v_permlane32_swap_b32_e32 v15, v17
	v_max_f32_e32 v17, v17, v17
	v_max_f32_e32 v15, v15, v15
	v_max_f32_e32 v15, v15, v17
	v_sub_f32_e32 v17, v15, v208
	v_mul_f32_e32 v17, 0x3d93cd3a, v17
	v_cmp_ge_f32_e32 vcc, s86, v17
	v_max_f32_e32 v17, v208, v208
	v_max_f32_e32 v17, v17, v15
	v_sub_f32_e32 v15, v208, v17
	v_mul_f32_e32 v15, 0x3dd53b94, v15
	v_exp_f32_e32 v15, v15
	s_cmp_eq_u64 vcc, exec
	s_cselect_b64 s[10:11], -1, 0
	s_waitcnt vmcnt(0)
	v_cndmask_b32_e64 v15, v15, 1.0, s[10:11]
	v_cmp_gt_f32_e32 vcc, 1.0, v15
	ds_write_b128 v202, v[6:9] offset:32768
	s_waitcnt vmcnt(1)
	ds_write_b128 v202, v[160:163] offset:45056
	s_waitcnt vmcnt(0)
	ds_write_b128 v203, v[164:167] offset:32768
	s_cbranch_vccz .LBB0_405
	s_and_saveexec_b64 s[78:79], s[8:9]
	ds_write_b32 v192, v15 offset:128
	s_or_b64 exec, exec, s[78:79]
	s_waitcnt lgkmcnt(0)
	ds_read_b128 v[18:21], v189 offset:224
	ds_read_b128 v[22:25], v189 offset:192
	ds_read_b128 v[26:29], v189 offset:160
	ds_read_b128 v[168:171], v189 offset:128
	s_waitcnt lgkmcnt(3)
	v_pk_mul_f32 v[94:95], v[94:95], v[20:21]
	s_waitcnt lgkmcnt(2)
	v_pk_mul_f32 v[90:91], v[90:91], v[24:25]
	s_waitcnt lgkmcnt(1)
	v_pk_mul_f32 v[86:87], v[86:87], v[28:29]
	s_waitcnt lgkmcnt(0)
	v_pk_mul_f32 v[82:83], v[82:83], v[170:171]
	v_pk_mul_f32 v[92:93], v[92:93], v[18:19]
	v_pk_mul_f32 v[88:89], v[88:89], v[22:23]
	v_pk_mul_f32 v[84:85], v[84:85], v[26:27]
	v_pk_mul_f32 v[80:81], v[80:81], v[168:169]
	v_pk_mul_f32 v[78:79], v[78:79], v[20:21]
	v_pk_mul_f32 v[74:75], v[74:75], v[24:25]
	v_pk_mul_f32 v[70:71], v[70:71], v[28:29]
	v_pk_mul_f32 v[66:67], v[66:67], v[170:171]
	v_pk_mul_f32 v[76:77], v[76:77], v[18:19]
	v_pk_mul_f32 v[72:73], v[72:73], v[22:23]
	v_pk_mul_f32 v[68:69], v[68:69], v[26:27]
	v_pk_mul_f32 v[64:65], v[64:65], v[168:169]
	v_pk_mul_f32 v[62:63], v[62:63], v[20:21]
	v_pk_mul_f32 v[58:59], v[58:59], v[24:25]
	v_pk_mul_f32 v[54:55], v[54:55], v[28:29]
	v_pk_mul_f32 v[50:51], v[50:51], v[170:171]
	v_pk_mul_f32 v[60:61], v[60:61], v[18:19]
	v_pk_mul_f32 v[56:57], v[56:57], v[22:23]
	v_pk_mul_f32 v[52:53], v[52:53], v[26:27]
	v_pk_mul_f32 v[48:49], v[48:49], v[168:169]
	v_pk_mul_f32 v[46:47], v[46:47], v[20:21]
	v_pk_mul_f32 v[42:43], v[42:43], v[24:25]
	v_pk_mul_f32 v[38:39], v[38:39], v[28:29]
	v_pk_mul_f32 v[34:35], v[34:35], v[170:171]
	v_pk_mul_f32 v[44:45], v[44:45], v[18:19]
	v_pk_mul_f32 v[40:41], v[40:41], v[22:23]
	v_pk_mul_f32 v[36:37], v[36:37], v[26:27]
	v_pk_mul_f32 v[32:33], v[32:33], v[168:169]
.LBB0_405:
	v_cndmask_b32_e64 v180, v17, v208, s[10:11]
	v_mul_f32_e32 v219, 0xbdd53b94, v180
	v_fmamk_f32 v17, v112, 0x3dd53b94, v219
	v_fmamk_f32 v18, v113, 0x3dd53b94, v219
	v_fmamk_f32 v19, v114, 0x3dd53b94, v219
	v_fmamk_f32 v20, v115, 0x3dd53b94, v219
	v_fmamk_f32 v21, v116, 0x3dd53b94, v219
	v_fmamk_f32 v22, v117, 0x3dd53b94, v219
	v_fmamk_f32 v23, v118, 0x3dd53b94, v219
	v_fmamk_f32 v24, v119, 0x3dd53b94, v219
	v_fmamk_f32 v25, v120, 0x3dd53b94, v219
	v_fmamk_f32 v26, v121, 0x3dd53b94, v219
	v_fmamk_f32 v27, v122, 0x3dd53b94, v219
	v_fmamk_f32 v28, v123, 0x3dd53b94, v219
	v_fmamk_f32 v29, v124, 0x3dd53b94, v219
	v_fmamk_f32 v30, v125, 0x3dd53b94, v219
	v_fmamk_f32 v31, v126, 0x3dd53b94, v219
	v_fmamk_f32 v112, v127, 0x3dd53b94, v219
	v_exp_f32_e32 v216, v17
	v_exp_f32_e32 v218, v18
	v_exp_f32_e32 v214, v19
	v_exp_f32_e32 v217, v20
	v_exp_f32_e32 v212, v21
	v_exp_f32_e32 v215, v22
	v_exp_f32_e32 v211, v23
	v_exp_f32_e32 v213, v24
	v_exp_f32_e32 v182, v25
	v_exp_f32_e32 v208, v26
	v_exp_f32_e32 v171, v27
	v_exp_f32_e32 v183, v28
	v_exp_f32_e32 v169, v29
	v_exp_f32_e32 v181, v30
	v_exp_f32_e32 v168, v31
	v_exp_f32_e32 v170, v112
	v_fmamk_f32 v220, v96, 0x3dd53b94, v219
	v_fmamk_f32 v221, v97, 0x3dd53b94, v219
	v_fmamk_f32 v222, v98, 0x3dd53b94, v219
	v_fmamk_f32 v223, v99, 0x3dd53b94, v219
	v_fmamk_f32 v224, v100, 0x3dd53b94, v219
	v_fmamk_f32 v225, v101, 0x3dd53b94, v219
	v_fmamk_f32 v226, v102, 0x3dd53b94, v219
	v_fmamk_f32 v227, v103, 0x3dd53b94, v219
	v_fmamk_f32 v228, v104, 0x3dd53b94, v219
	v_fmamk_f32 v229, v105, 0x3dd53b94, v219
	v_fmamk_f32 v230, v106, 0x3dd53b94, v219
	v_fmamk_f32 v231, v107, 0x3dd53b94, v219
	v_fmamk_f32 v232, v108, 0x3dd53b94, v219
	v_fmamk_f32 v233, v109, 0x3dd53b94, v219
	v_fmamk_f32 v234, v110, 0x3dd53b94, v219
	v_fmac_f32_e32 v219, 0x3dd53b94, v111
	s_add_i32 s10, s54, 1
	s_waitcnt lgkmcnt(0)
	s_barrier
	ds_write_b128 v200, v[2:5]
	ds_write_b128 v201, v[10:13]
	s_cmp_gt_i32 s10, s5
	s_cbranch_scc1 .LBB0_407
	ds_read_b128 v[236:239], v196 offset:32768
	ds_read_b128 v[240:243], v196 offset:45056
	ds_read_b128 v[246:249], v197 offset:32768
	ds_read_b128 v[250:253], v197 offset:45056
	ds_read_b128 v[6:9], v195
	ds_read_b128 v[10:13], v195 offset:1024
	ds_read_b128 v[2:5], v195 offset:2048
	v_cvt_pk_bf16_f32 v18, v216, v218
	v_cvt_pk_bf16_f32 v19, v214, v217
	v_cvt_pk_bf16_f32 v20, v212, v215
	v_cvt_pk_bf16_f32 v21, v211, v213
	v_cvt_pk_bf16_f32 v22, v182, v208
	v_cvt_pk_bf16_f32 v23, v171, v183
	v_cvt_pk_bf16_f32 v24, v169, v181
	v_cvt_pk_bf16_f32 v25, v168, v170
	v_add_f32_e32 v17, 0, v216
	v_add_f32_e32 v17, v218, v17
	v_add_f32_e32 v17, v214, v17
	v_add_f32_e32 v17, v217, v17
	v_add_f32_e32 v17, v212, v17
	v_add_f32_e32 v17, v215, v17
	v_add_f32_e32 v17, v211, v17
	v_add_f32_e32 v17, v213, v17
	s_waitcnt lgkmcnt(6)
	v_mfma_f32_32x32x16_bf16 v[112:127], v[236:239], v[156:159], 0
	ds_read_b128 v[236:239], v199 offset:32768
	v_add_f32_e32 v17, v182, v17
	v_add_f32_e32 v17, v208, v17
	v_permlane32_swap_b32_e32 v18, v20
	s_waitcnt lgkmcnt(6)
	v_mfma_f32_32x32x16_bf16 v[96:111], v[240:243], v[156:159], 0
	ds_read_b128 v[240:243], v199 offset:45056
	v_add_f32_e32 v17, v171, v17
	v_add_f32_e32 v17, v183, v17
	v_permlane32_swap_b32_e32 v19, v21
	s_waitcnt lgkmcnt(6)
	v_mfma_f32_32x32x16_bf16 v[112:127], v[246:249], v[152:155], v[112:127]
	ds_read_b128 v[246:249], v198 offset:32768
	v_add_f32_e32 v17, v169, v17
	v_add_f32_e32 v17, v181, v17
	s_waitcnt lgkmcnt(6)
	v_mfma_f32_32x32x16_bf16 v[96:111], v[250:253], v[152:155], v[96:111]
	ds_read_b128 v[250:253], v198 offset:45056
	v_permlane32_swap_b32_e32 v22, v24
	v_add_f32_e32 v17, v168, v17
	s_waitcnt lgkmcnt(3)
	v_mfma_f32_32x32x16_bf16 v[112:127], v[236:239], v[148:151], v[112:127]
	ds_read_b128 v[236:239], v196 offset:32896
	v_add_f32_e32 v17, v170, v17
	v_permlane32_swap_b32_e32 v23, v25
	s_waitcnt lgkmcnt(3)
	v_mfma_f32_32x32x16_bf16 v[96:111], v[240:243], v[148:151], v[96:111]
	ds_read_b128 v[240:243], v196 offset:45184
	v_exp_f32_e32 v220, v220
	v_exp_f32_e32 v221, v221
	s_waitcnt lgkmcnt(3)
	v_mfma_f32_32x32x16_bf16 v[112:127], v[246:249], v[144:147], v[112:127]
	ds_read_b128 v[246:249], v197 offset:32896
	v_exp_f32_e32 v222, v222
	v_exp_f32_e32 v223, v223
	s_waitcnt lgkmcnt(3)
	v_mfma_f32_32x32x16_bf16 v[96:111], v[250:253], v[144:147], v[96:111]
	ds_read_b128 v[250:253], v197 offset:45184
	v_add_f32_e32 v17, v220, v17
	v_exp_f32_e32 v224, v224
	s_waitcnt lgkmcnt(3)
	v_mfma_f32_32x32x16_bf16 v[112:127], v[236:239], v[140:143], v[112:127]
	ds_read_b128 v[236:239], v199 offset:32896
	v_add_f32_e32 v17, v221, v17
	v_exp_f32_e32 v225, v225
	s_waitcnt lgkmcnt(3)
	v_mfma_f32_32x32x16_bf16 v[96:111], v[240:243], v[140:143], v[96:111]
	ds_read_b128 v[240:243], v199 offset:45184
	v_add_f32_e32 v17, v222, v17
	v_exp_f32_e32 v226, v226
	s_waitcnt lgkmcnt(3)
	v_mfma_f32_32x32x16_bf16 v[112:127], v[246:249], v[136:139], v[112:127]
	ds_read_b128 v[246:249], v198 offset:32896
	v_add_f32_e32 v17, v223, v17
	v_exp_f32_e32 v227, v227
	s_waitcnt lgkmcnt(3)
	v_mfma_f32_32x32x16_bf16 v[96:111], v[250:253], v[136:139], v[96:111]
	ds_read_b128 v[250:253], v198 offset:45184
	v_cvt_pk_bf16_f32 v26, v220, v221
	v_cvt_pk_bf16_f32 v27, v222, v223
	s_waitcnt lgkmcnt(3)
	v_mfma_f32_32x32x16_bf16 v[112:127], v[236:239], v[132:135], v[112:127]
	ds_read_b128 v[236:239], v196 offset:33024
	v_add_f32_e32 v17, v224, v17
	v_exp_f32_e32 v228, v228
	s_waitcnt lgkmcnt(3)
	v_mfma_f32_32x32x16_bf16 v[96:111], v[240:243], v[132:135], v[96:111]
	ds_read_b128 v[240:243], v196 offset:45312
	v_add_f32_e32 v17, v225, v17
	v_exp_f32_e32 v229, v229
	s_waitcnt lgkmcnt(3)
	v_mfma_f32_32x32x16_bf16 v[112:127], v[246:249], v[128:131], v[112:127]
	ds_read_b128 v[246:249], v197 offset:33024
	v_add_f32_e32 v17, v226, v17
	v_exp_f32_e32 v230, v230
	s_waitcnt lgkmcnt(3)
	v_mfma_f32_32x32x16_bf16 v[96:111], v[250:253], v[128:131], v[96:111]
	ds_read_b128 v[250:253], v197 offset:45312
	v_add_f32_e32 v17, v227, v17
	v_exp_f32_e32 v231, v231
	s_waitcnt lgkmcnt(3)
	v_mfma_f32_32x32x16_bf16 v[112:127], v[236:239], v[6:9], v[112:127]
	ds_read_b128 v[236:239], v199 offset:33024
	v_cvt_pk_bf16_f32 v28, v224, v225
	v_cvt_pk_bf16_f32 v29, v226, v227
	s_waitcnt lgkmcnt(3)
	v_mfma_f32_32x32x16_bf16 v[96:111], v[240:243], v[6:9], v[96:111]
	ds_read_b128 v[240:243], v199 offset:45312
	ds_read_b128 v[6:9], v195 offset:3072
	v_add_f32_e32 v17, v228, v17
	v_exp_f32_e32 v232, v232
	s_waitcnt lgkmcnt(4)
	v_mfma_f32_32x32x16_bf16 v[112:127], v[246:249], v[10:13], v[112:127]
	ds_read_b128 v[246:249], v198 offset:33024
	v_permlane32_swap_b32_e32 v26, v28
	v_permlane32_swap_b32_e32 v27, v29
	s_waitcnt lgkmcnt(4)
	v_mfma_f32_32x32x16_bf16 v[96:111], v[250:253], v[10:13], v[96:111]
	ds_read_b128 v[250:253], v198 offset:45312
	v_add_f32_e32 v17, v229, v17
	v_exp_f32_e32 v233, v233
	s_waitcnt lgkmcnt(4)
	v_mfma_f32_32x32x16_bf16 v[112:127], v[236:239], v[2:5], v[112:127]
	v_add_f32_e32 v17, v230, v17
	v_exp_f32_e32 v234, v234
	s_waitcnt lgkmcnt(3)
	v_mfma_f32_32x32x16_bf16 v[96:111], v[240:243], v[2:5], v[96:111]
	v_add_f32_e32 v17, v231, v17
	v_exp_f32_e32 v219, v219
	s_waitcnt lgkmcnt(1)
	v_mfma_f32_32x32x16_bf16 v[112:127], v[246:249], v[6:9], v[112:127]
	v_cvt_pk_bf16_f32 v168, v228, v229
	v_cvt_pk_bf16_f32 v169, v230, v231
	s_waitcnt lgkmcnt(0)
	v_mfma_f32_32x32x16_bf16 v[96:111], v[250:253], v[6:9], v[96:111]
	v_add_f32_e32 v17, v232, v17
	v_add_f32_e32 v17, v233, v17
	v_add_f32_e32 v17, v234, v17
	v_add_f32_e32 v17, v219, v17
	v_cvt_pk_bf16_f32 v170, v232, v233
	v_cvt_pk_bf16_f32 v171, v234, v219
	v_mov_b32_e32 v30, v17
	s_nop 1
	v_permlane32_swap_b32_e32 v168, v170
	v_permlane32_swap_b32_e32 v169, v171
	v_permlane32_swap_b32_e32 v17, v30
	s_branch .Lattn_h2_join

.LBB0_412:
	v_max_f32_e32 v18, v113, v113
	v_max_f32_e32 v19, v112, v112
	v_max_f32_e32 v18, v19, v18
	v_max3_f32 v18, v18, v114, v115
	v_max3_f32 v18, v18, v116, v117
	v_max3_f32 v18, v18, v118, v119
	v_max3_f32 v18, v18, v120, v121
	v_max3_f32 v18, v18, v122, v123
	v_max3_f32 v18, v18, v124, v125
	v_max3_f32 v18, v18, v126, v127
	v_max3_f32 v18, v18, v96, v97
	v_max3_f32 v18, v18, v98, v99
	v_max3_f32 v18, v18, v100, v101
	v_max3_f32 v18, v18, v102, v103
	v_max3_f32 v18, v18, v104, v105
	v_max3_f32 v18, v18, v106, v107
	v_max3_f32 v18, v18, v108, v109
	v_max3_f32 v18, v18, v110, v111
	v_mov_b32_e32 v19, v18
	s_nop 1
	v_permlane32_swap_b32_e32 v18, v19
	v_max_f32_e32 v19, v19, v19
	v_max_f32_e32 v18, v18, v18
	v_max_f32_e32 v18, v18, v19
	v_sub_f32_e32 v19, v18, v180
	v_mul_f32_e32 v19, 0x3d93cd3a, v19
	v_cmp_ge_f32_e32 vcc, s86, v19
	s_cmp_eq_u64 vcc, exec
	s_cselect_b64 s[10:11], -1, 0
	s_andn2_b64 vcc, exec, s[78:79]
	s_cbranch_vccnz .LBB0_414
	s_waitcnt vmcnt(0)
	ds_write_b128 v209, v[6:9]
	s_waitcnt vmcnt(1)
	ds_write_b128 v209, v[160:163] offset:12288
	s_waitcnt vmcnt(0)
	ds_write_b128 v203, v[164:167] offset:57344
.LBB0_414:
	s_waitcnt vmcnt(4)
	v_max_f32_e32 v235, v180, v180
	v_max_f32_e32 v245, v235, v18
	v_sub_f32_e32 v235, v180, v245
	v_mul_f32_e32 v235, 0x3dd53b94, v235
	v_exp_f32_e32 v235, v235
	s_nop 0
	v_cndmask_b32_e64 v235, v235, 1.0, s[10:11]
	v_cmp_gt_f32_e32 vcc, 1.0, v235
	s_cbranch_vccz .LBB0_393
	s_and_saveexec_b64 s[76:77], s[8:9]
	s_cbranch_execz .LBB0_392
	ds_write_b32 v192, v235 offset:128
	s_branch .LBB0_392

.LBB0_427:
	v_max_f32_e32 v2, v113, v113
	v_max_f32_e32 v3, v112, v112
	v_max_f32_e32 v2, v3, v2
	v_max3_f32 v2, v2, v114, v115
	v_max3_f32 v2, v2, v116, v117
	v_max3_f32 v2, v2, v118, v119
	v_max3_f32 v2, v2, v120, v121
	v_max3_f32 v2, v2, v122, v123
	v_max3_f32 v2, v2, v124, v125
	v_max3_f32 v2, v2, v126, v127
	v_max3_f32 v2, v2, v96, v97
	v_max3_f32 v2, v2, v98, v99
	v_max3_f32 v2, v2, v100, v101
	v_max3_f32 v2, v2, v102, v103
	v_max3_f32 v2, v2, v104, v105
	v_max3_f32 v2, v2, v106, v107
	v_max3_f32 v2, v2, v108, v109
	v_max3_f32 v2, v2, v110, v111
	v_mov_b32_e32 v3, v2
	s_nop 1
	v_permlane32_swap_b32_e32 v2, v3
	v_max_f32_e32 v3, v3, v3
	v_max_f32_e32 v2, v2, v2
	v_max_f32_e32 v2, v2, v3
	v_max_f32_e32 v4, v208, v208
	v_sub_f32_e32 v3, v2, v208
	v_max_f32_e32 v2, v4, v2
	v_sub_f32_e32 v4, v208, v2
	v_mul_f32_e32 v4, 0x3dd53b94, v4
	v_mul_f32_e32 v3, 0x3d93cd3a, v3
	v_exp_f32_e32 v4, v4
	v_cmp_ge_f32_e32 vcc, s86, v3
	s_cmp_eq_u64 vcc, exec
	s_cselect_b64 s[8:9], -1, 0
	v_cndmask_b32_e64 v15, v4, 1.0, s[8:9]
	v_cmp_gt_f32_e32 vcc, 1.0, v15
	s_waitcnt lgkmcnt(0)
	s_barrier
	s_cbranch_vccz .LBB0_431
	v_cmp_gt_u32_e32 vcc, 32, v186
	s_and_saveexec_b64 s[76:77], vcc
	ds_write_b32 v192, v15 offset:128
	s_or_b64 exec, exec, s[76:77]
	s_waitcnt lgkmcnt(0)
	ds_read_b128 v[4:7], v189 offset:224
	ds_read_b128 v[8:11], v189 offset:192
	ds_read_b128 v[18:21], v189 offset:160
	ds_read_b128 v[22:25], v189 offset:128
	s_waitcnt lgkmcnt(3)
	v_pk_mul_f32 v[94:95], v[94:95], v[6:7]
	s_waitcnt lgkmcnt(2)
	v_pk_mul_f32 v[90:91], v[90:91], v[10:11]
	s_waitcnt lgkmcnt(1)
	v_pk_mul_f32 v[86:87], v[86:87], v[20:21]
	s_waitcnt lgkmcnt(0)
	v_pk_mul_f32 v[82:83], v[82:83], v[24:25]
	v_pk_mul_f32 v[92:93], v[92:93], v[4:5]
	v_pk_mul_f32 v[88:89], v[88:89], v[8:9]
	v_pk_mul_f32 v[84:85], v[84:85], v[18:19]
	v_pk_mul_f32 v[80:81], v[80:81], v[22:23]
	v_pk_mul_f32 v[78:79], v[78:79], v[6:7]
	v_pk_mul_f32 v[74:75], v[74:75], v[10:11]
	v_pk_mul_f32 v[70:71], v[70:71], v[20:21]
	v_pk_mul_f32 v[66:67], v[66:67], v[24:25]
	v_pk_mul_f32 v[76:77], v[76:77], v[4:5]
	v_pk_mul_f32 v[72:73], v[72:73], v[8:9]
	v_pk_mul_f32 v[68:69], v[68:69], v[18:19]
	v_pk_mul_f32 v[64:65], v[64:65], v[22:23]
	v_pk_mul_f32 v[62:63], v[62:63], v[6:7]
	v_pk_mul_f32 v[58:59], v[58:59], v[10:11]
	v_pk_mul_f32 v[54:55], v[54:55], v[20:21]
	v_pk_mul_f32 v[50:51], v[50:51], v[24:25]
	v_pk_mul_f32 v[60:61], v[60:61], v[4:5]
	v_pk_mul_f32 v[56:57], v[56:57], v[8:9]
	v_pk_mul_f32 v[52:53], v[52:53], v[18:19]
	v_pk_mul_f32 v[48:49], v[48:49], v[22:23]
	v_pk_mul_f32 v[46:47], v[46:47], v[6:7]
	v_pk_mul_f32 v[42:43], v[42:43], v[10:11]
	v_pk_mul_f32 v[38:39], v[38:39], v[20:21]
	v_pk_mul_f32 v[34:35], v[34:35], v[24:25]
	v_pk_mul_f32 v[44:45], v[44:45], v[4:5]
	v_pk_mul_f32 v[40:41], v[40:41], v[8:9]
	v_pk_mul_f32 v[36:37], v[36:37], v[18:19]
	v_pk_mul_f32 v[32:33], v[32:33], v[22:23]

	.amdhsa_kernel _Z13mla_hgrn2_fwd6Params
		.amdhsa_group_segment_fixed_size 0
		.amdhsa_private_segment_fixed_size 0
		.amdhsa_kernarg_size 520
		.amdhsa_user_sgpr_count 2
		.amdhsa_user_sgpr_dispatch_ptr 0
		.amdhsa_user_sgpr_queue_ptr 0
		.amdhsa_user_sgpr_kernarg_segment_ptr 1
		.amdhsa_user_sgpr_dispatch_id 0
		.amdhsa_user_sgpr_kernarg_preload_length 0
		.amdhsa_user_sgpr_kernarg_preload_offset 0
		.amdhsa_user_sgpr_private_segment_size 0
		.amdhsa_uses_dynamic_stack 0
		.amdhsa_enable_private_segment 0
		.amdhsa_system_sgpr_workgroup_id_x 1
		.amdhsa_system_sgpr_workgroup_id_y 0
		.amdhsa_system_sgpr_workgroup_id_z 0
		.amdhsa_system_sgpr_workgroup_info 0
		.amdhsa_system_vgpr_workitem_id 2
		.amdhsa_next_free_vgpr 256
		.amdhsa_next_free_sgpr 98
		.amdhsa_accum_offset 256
		.amdhsa_reserve_vcc 1
		.amdhsa_float_round_mode_32 0
		.amdhsa_float_round_mode_16_64 0
		.amdhsa_float_denorm_mode_32 3
		.amdhsa_float_denorm_mode_16_64 3
		.amdhsa_dx10_clamp 1
		.amdhsa_ieee_mode 1
		.amdhsa_fp16_overflow 0
		.amdhsa_tg_split 0
		.amdhsa_exception_fp_ieee_invalid_op 0
		.amdhsa_exception_fp_denorm_src 0
		.amdhsa_exception_fp_ieee_div_zero 0
		.amdhsa_exception_fp_ieee_overflow 0
		.amdhsa_exception_fp_ieee_underflow 0
		.amdhsa_exception_fp_ieee_inexact 0
		.amdhsa_exception_int_div_zero 0
	.end_amdhsa_kernel

amdhsa.kernels:
  - .agpr_count:     0
    .args:
      - .offset:         0
        .size:           264
        .value_kind:     by_value
      - .offset:         264
        .size:           4
        .value_kind:     hidden_block_count_x
      - .offset:         268
        .size:           4
        .value_kind:     hidden_block_count_y
      - .offset:         272
        .size:           4
        .value_kind:     hidden_block_count_z
      - .offset:         276
        .size:           2
        .value_kind:     hidden_group_size_x
      - .offset:         278
        .size:           2
        .value_kind:     hidden_group_size_y
      - .offset:         280
        .size:           2
        .value_kind:     hidden_group_size_z
      - .offset:         282
        .size:           2
        .value_kind:     hidden_remainder_x
      - .offset:         284
        .size:           2
        .value_kind:     hidden_remainder_y
      - .offset:         286
        .size:           2
        .value_kind:     hidden_remainder_z
      - .offset:         304
        .size:           8
        .value_kind:     hidden_global_offset_x
      - .offset:         312
        .size:           8
        .value_kind:     hidden_global_offset_y
      - .offset:         320
        .size:           8
        .value_kind:     hidden_global_offset_z
      - .offset:         328
        .size:           2
        .value_kind:     hidden_grid_dims
      - .offset:         352
        .size:           8
        .value_kind:     hidden_multigrid_sync_arg
      - .offset:         384
        .size:           4
        .value_kind:     hidden_dynamic_lds_size
    .group_segment_fixed_size: 0
    .kernarg_segment_align: 8
    .kernarg_segment_size: 520
    .language:       OpenCL C
    .language_version:
      - 2
      - 0
    .max_flat_workgroup_size: 512
    .name:           _Z13mla_hgrn2_fwd6Params
    .private_segment_fixed_size: 0
    .sgpr_count:     104
    .sgpr_spill_count: 10
    .symbol:         _Z13mla_hgrn2_fwd6Params.kd
    .uniform_work_group_size: 1
    .uses_dynamic_stack: false
    .vgpr_count:     256
    .vgpr_spill_count: 0
    .wavefront_size: 64
